# attention QK^T MFMAs consume the K fragments in LDS-return order (two interleaved accumulate chains, counted lgkmcnt) on top of v80
# speedup vs baseline: 1.0107x; 1.0050x over previous
.Latt_k_done:
	s_waitcnt lgkmcnt(14)
	v_mfma_f32_16x16x32_bf16 v[128:131], v[84:87], v[4:7], 0
	v_mfma_f32_16x16x32_bf16 v[124:127], v[88:91], v[4:7], 0
	s_waitcnt lgkmcnt(12)
	v_mfma_f32_16x16x32_bf16 v[128:131], v[92:95], v[8:11], v[128:131]
	v_mfma_f32_16x16x32_bf16 v[124:127], v[96:99], v[8:11], v[124:127]
	s_waitcnt lgkmcnt(10)
	v_mfma_f32_16x16x32_bf16 v[128:131], v[100:103], v[12:15], v[128:131]
	v_mfma_f32_16x16x32_bf16 v[124:127], v[104:107], v[12:15], v[124:127]
	s_waitcnt lgkmcnt(8)
	v_mfma_f32_16x16x32_bf16 v[128:131], v[108:111], v[16:19], v[128:131]
	v_mfma_f32_16x16x32_bf16 v[124:127], v[112:115], v[16:19], v[124:127]
	s_waitcnt lgkmcnt(6)
	v_mfma_f32_16x16x32_bf16 v[84:87], v[116:119], v[4:7], 0
	v_mfma_f32_16x16x32_bf16 v[92:95], v[166:169], v[4:7], 0
	s_waitcnt lgkmcnt(4)
	v_mfma_f32_16x16x32_bf16 v[84:87], v[120:123], v[8:11], v[84:87]
	v_mfma_f32_16x16x32_bf16 v[92:95], v[170:173], v[8:11], v[92:95]
	s_waitcnt lgkmcnt(2)
	v_mfma_f32_16x16x32_bf16 v[84:87], v[174:177], v[12:15], v[84:87]
	v_mfma_f32_16x16x32_bf16 v[92:95], v[178:181], v[12:15], v[92:95]
	s_waitcnt lgkmcnt(0)
	v_mfma_f32_16x16x32_bf16 v[120:123], v[182:185], v[16:19], v[84:87]
	v_mfma_f32_16x16x32_bf16 v[116:119], v[186:189], v[16:19], v[92:95]
	v_add_u32_e32 v2, s71, v157
	v_add_u32_e32 v3, v2, v158
	v_add_u32_e32 v145, v2, v159
	ds_read_b128 v[100:103], v3
	ds_read_b128 v[88:91], v3 offset:2048
	ds_read_b128 v[112:115], v145
	ds_read_b128 v[104:107], v145 offset:2048
	ds_read_b128 v[92:95], v3 offset:4096
	ds_read_b128 v[84:87], v3 offset:6144
	ds_read_b128 v[108:111], v145 offset:4096
	ds_read_b128 v[96:99], v145 offset:6144
	ds_read_b128 v[194:197], v3 offset:8192
	ds_read_b128 v[198:201], v3 offset:10240
	ds_read_b128 v[202:205], v145 offset:8192
	ds_read_b128 v[206:209], v145 offset:10240
	ds_read_b128 v[210:213], v3 offset:12288
	ds_read_b128 v[214:217], v3 offset:14336
	ds_read_b128 v[218:221], v145 offset:12288
	ds_read_b128 v[222:225], v145 offset:14336
	s_cmp_lt_i32 s70, s69
	s_cbranch_scc0 .Latt_v_done
	s_xor_b32 s0, s71, 0x8000
	v_lshl_add_u64 v[186:187], s[48:49], 0, v[148:149]
	s_add_i32 s0, s80, s0
	v_lshl_add_u64 v[188:189], v[186:187], 0, s[60:61]
	s_mov_b32 m0, s0
	s_nop 0
	global_load_lds_dwordx4 v[188:189], off
	v_lshl_add_u64 v[188:189], v[186:187], 0, s[62:63]
	s_add_i32 m0, s0, 0x2000
	s_nop 0
	global_load_lds_dwordx4 v[188:189], off
	v_lshl_add_u64 v[188:189], v[186:187], 0, s[64:65]
	s_add_i32 m0, s0, 0x4000
	v_lshl_add_u64 v[186:187], v[186:187], 0, s[66:67]
	global_load_lds_dwordx4 v[188:189], off
	s_add_i32 m0, s0, 0x6000
	s_nop 0
	global_load_lds_dwordx4 v[186:187], off
